# GEMM phase prologue: K-tile 1 loads issued together with K-tile 0 loads (one exposed memory round trip instead of two per GEMM phase), on top of v13
# baseline (speedup 1.0000x reference)
.LBB0_419:
	s_add_i32 m0, s11, 0x18000
	v_lshl_add_u64 v[8:9], v[8:9], 0, s[60:61]
	global_load_lds_dwordx4 v[8:9], off
	v_lshl_add_u64 v[4:5], v[4:5], 0, s[60:61]
	s_add_i32 m0, s11, 0x1a000
	s_add_i32 s31, s11, 0x8000
	global_load_lds_dwordx4 v[4:5], off
	v_lshl_add_u64 v[4:5], v[6:7], 0, s[60:61]
	s_mov_b32 m0, s31
	s_add_i32 s18, s11, 0xa000
	global_load_lds_dwordx4 v[4:5], off
	v_lshl_add_u64 v[4:5], v[10:11], 0, s[60:61]
	s_mov_b32 m0, s18
	v_lshl_add_u64 v[2:3], v[2:3], 0, s[60:61]
	global_load_lds_dwordx4 v[4:5], off
	s_add_i32 m0, s11, 0x1c000
	v_lshl_add_u64 v[0:1], v[0:1], 0, s[60:61]
	global_load_lds_dwordx4 v[2:3], off
	s_add_i32 m0, s11, 0x1e000
	s_movk_i32 s21, 0x3c0
	global_load_lds_dwordx4 v[0:1], off
	s_waitcnt vmcnt(8)
	s_barrier
	v_and_b32_e32 v0, 48, v196
	v_lshlrev_b32_e32 v1, 6, v196
	s_and_b32 s17, s17, 3
	v_and_or_b32 v0, v1, s21, v0
	v_lshlrev_b32_e32 v1, 2, v196
	s_lshl_b32 s19, s20, 6
	s_lshl_b32 s20, s20, 13
	v_and_b32_e32 v1, 32, v1
	s_lshl_b32 s21, s17, 12
	v_bitop3_b32 v2, v0, s20, v1 bitop3:0xde
	s_lshl_b32 s20, s17, 5
	v_bitop3_b32 v186, s21, v0, v1 bitop3:0xf6
	s_add_i32 s21, s88, -2
	s_cmpk_lt_u32 s16, 0x100
	s_cselect_b64 s[28:29], -1, 0
	s_cmp_eq_u32 s17, 0
	s_cselect_b64 s[0:1], -1, 0
	v_writelane_b32 v255, s0, 26
	s_lshl_b32 s91, s17, 1
	s_ashr_i32 s89, s72, 31
	v_writelane_b32 v255, s1, 27
	s_lshr_b32 s0, s22, 3
	s_ashr_i32 s87, s66, 31
	s_and_b32 s86, s22, 4
	v_writelane_b32 v255, s0, 28
	s_add_i32 s0, s0, 1
	s_lshr_b32 s64, s58, 6
	s_and_b64 s[2:3], s[2:3], exec
	v_cvt_f32_u32_e32 v0, s64
	s_mov_b32 s2, 0x5180000
	v_writelane_b32 v255, s0, 30
	s_cselect_b32 s2, s2, 0x9380000
	s_and_b64 s[0:1], s[44:45], exec
	s_mov_b32 s0, 0xd580000
	s_cselect_b32 s3, s0, 0x11780000
	s_and_b64 s[0:1], s[4:5], exec
	v_rcp_iflag_f32_e32 v0, v0
	v_writelane_b32 v255, s58, 32
	s_cselect_b32 s0, 0x19b0000, s3
	v_writelane_b32 v255, s0, 33
	s_and_b64 s[0:1], s[34:35], exec
	s_cselect_b32 s34, 0xd580000, s2
	s_add_u32 s0, s12, 0x19160000
	s_addc_u32 s1, s13, 0
	v_mul_f32_e32 v0, 0x4f7ffffe, v0
	v_writelane_b32 v255, s0, 34
	v_cvt_u32_f32_e32 v0, v0
	s_waitcnt vmcnt(6)
	s_mov_b32 s97, 0
	v_writelane_b32 v255, s1, 35
	s_add_u32 s0, s12, 0x18460000
	s_addc_u32 s1, s13, 0
	v_writelane_b32 v255, s0, 36
	s_mov_b32 s23, s53
	v_add_u32_e32 v187, 0, v2
	v_writelane_b32 v255, s1, 37
	s_sub_i32 s0, 0, s64
	v_readfirstlane_b32 s1, v0
	s_mul_i32 s0, s0, s1
	s_mul_hi_u32 s0, s1, s0
	s_add_i32 s0, s1, s0
	v_writelane_b32 v255, s0, 38
	s_add_u32 s0, s24, 0x80
	v_add_u32_e32 v0, v14, v12
	s_addc_u32 s1, 0, 0
	v_add_lshl_u32 v98, v0, v13, 1
	v_add_u32_e32 v0, v17, v15
	v_lshl_add_u64 v[162:163], s[0:1], 0, v[98:99]
	v_add_lshl_u32 v98, v0, v16, 1
	v_lshl_add_u64 v[164:165], s[0:1], 0, v[98:99]
	s_barrier
	s_waitcnt vmcnt(0)
	s_branch .LBB0_422
